# v16 + attention and SSD output stages: serial load chains batched (one wait, none between stores) + LayerNorm dead index code removed + no mid-segment setprio flips
# speedup vs baseline: 1.0032x; 1.0005x over previous
; DI unsigned pk2(float lo, float hi) { f32x2 v = {lo, hi}; bf16x2_t b = __builtin_convertvector(v, bf16x2_t); return __builtin_bit_cast(unsigned, b); }
; DI void s3_ssd_unit(LAS unsigned char* lds, int tid, const ScanCtx& C, int b, int vc) {
;     ...
;     if (hi == 0) stat[tq_ * 2 + pt] = ssq;
;     __syncthreads();
;     const float rn = 1.0f / sqrtf((stat[tq_ * 2] + stat[tq_ * 2 + 1]) * (1.0f / 256.0f) + 1e-6f);
; #pragma unroll
;     for (int h = 0; h < 4; ++h)
; #pragma unroll
;         for (int g4 = 0; g4 < 4; ++g4) {
;             const int p = pt * 32 + 8 * g4 + 4 * hi;
;             const f32x4 gv = *(const f32x4*)(C.ssmg + h * 64 + p);
;             u32x2* mp = (u32x2*)(C.MG + (size_t)rowq * DM + 512 + h * 64 + p);
;             const u32x2 v = *mp;
;             u32x2 w; w.x = pk2(bflo(v.x) * rn * gv.x, bfhi(v.x) * rn * gv.y); w.y = pk2(bflo(v.y) * rn * gv.z, bfhi(v.y) * rn * gv.w);
;             *mp = w;
;         }
.LBB0_351:
	s_or_b64 exec, exec, s[0:1]
	v_add_u32_e32 v0, 0, v0
	s_waitcnt lgkmcnt(0)
	s_barrier
	ds_read_b64 v[0:1], v0 offset:8192
	s_mov_b32 s0, 0xf800000
	v_readlane_b32 s6, v254, 11
	v_readlane_b32 s70, v254, 3
	v_readlane_b32 s74, v254, 5
	s_waitcnt lgkmcnt(0)
	v_add_f32_e32 v0, v0, v1
	v_mov_b32_e32 v1, 0x358637bd
	v_fmamk_f32 v0, v0, 0x3b800000, v1
	v_cmp_gt_f32_e32 vcc, s0, v0
	v_mul_f32_e32 v1, 0x4f800000, v0
	v_readlane_b32 s28, v254, 7
	v_cndmask_b32_e32 v0, v0, v1, vcc
	v_sqrt_f32_e32 v1, v0
	v_readlane_b32 s30, v254, 9
	s_movk_i32 s72, 0x1c00
	s_movk_i32 s66, 0xffe0
	v_add_u32_e32 v2, -1, v1
	v_fma_f32 v3, -v2, v1, v0
	v_cmp_ge_f32_e64 s[0:1], 0, v3
	v_add_u32_e32 v3, 1, v1
	s_movk_i32 s73, 0x110
	v_cndmask_b32_e64 v2, v1, v2, s[0:1]
	v_fma_f32 v1, -v3, v1, v0
	v_cmp_lt_f32_e64 s[0:1], 0, v1
	s_movk_i32 s67, 0x600
	v_readlane_b32 s71, v254, 4
	v_cndmask_b32_e64 v1, v2, v3, s[0:1]
	v_mul_f32_e32 v2, 0x37800000, v1
	v_cndmask_b32_e32 v1, v1, v2, vcc
	v_cmp_class_f32_e32 vcc, v0, v208
	v_readlane_b32 s75, v254, 6
	v_readlane_b32 s29, v254, 8
	v_cndmask_b32_e32 v0, v1, v0, vcc
	v_div_scale_f32 v1, s[0:1], v0, v0, 1.0
	v_rcp_f32_e32 v2, v1
	v_readlane_b32 s0, v254, 0
	v_readlane_b32 s1, v254, 1
	v_readlane_b32 s31, v254, 10
	v_fma_f32 v3, -v1, v2, 1.0
	v_fmac_f32_e32 v2, v3, v2
	v_div_scale_f32 v3, vcc, 1.0, v0, 1.0
	v_mul_f32_e32 v4, v3, v2
	v_fma_f32 v5, -v1, v4, v3
	v_fmac_f32_e32 v4, v5, v2
	v_fma_f32 v1, -v1, v4, v3
	v_div_fmas_f32 v1, v1, v2, v4
	v_div_fixup_f32 v0, v1, v0, 1.0
	v_lshlrev_b32_e32 v1, 2, v94
	global_load_dwordx4 v[2:5], v1, s[0:1]
	global_load_dwordx2 v[6:7], v[80:81], off offset:1024
	global_load_dwordx4 v[96:99], v1, s[0:1] offset:32
	global_load_dwordx2 v[100:101], v[80:81], off offset:1040
	global_load_dwordx4 v[102:105], v1, s[0:1] offset:64
	global_load_dwordx2 v[106:107], v[80:81], off offset:1056
	global_load_dwordx4 v[108:111], v1, s[0:1] offset:96
	global_load_dwordx2 v[112:113], v[80:81], off offset:1072
	global_load_dwordx4 v[114:117], v1, s[0:1] offset:256
	global_load_dwordx2 v[118:119], v[80:81], off offset:1152
	global_load_dwordx4 v[120:123], v1, s[0:1] offset:288
	global_load_dwordx2 v[124:125], v[80:81], off offset:1168
	global_load_dwordx4 v[126:129], v1, s[0:1] offset:320
	global_load_dwordx2 v[130:131], v[80:81], off offset:1184
	global_load_dwordx4 v[132:135], v1, s[0:1] offset:352
	global_load_dwordx2 v[136:137], v[80:81], off offset:1200
	global_load_dwordx4 v[138:141], v1, s[0:1] offset:512
	global_load_dwordx2 v[142:143], v[80:81], off offset:1280
	global_load_dwordx4 v[160:163], v1, s[0:1] offset:544
	global_load_dwordx2 v[164:165], v[80:81], off offset:1296
	global_load_dwordx4 v[168:171], v1, s[0:1] offset:576
	global_load_dwordx2 v[172:173], v[80:81], off offset:1312
	global_load_dwordx4 v[174:177], v1, s[0:1] offset:608
	global_load_dwordx2 v[178:179], v[80:81], off offset:1328
	global_load_dwordx4 v[180:183], v1, s[0:1] offset:768
	global_load_dwordx2 v[184:185], v[80:81], off offset:1408
	global_load_dwordx4 v[186:189], v1, s[0:1] offset:800
	global_load_dwordx2 v[190:191], v[80:81], off offset:1424
	global_load_dwordx4 v[192:195], v1, s[0:1] offset:832
	global_load_dwordx2 v[196:197], v[80:81], off offset:1440
	global_load_dwordx4 v[198:201], v1, s[0:1] offset:864
	global_load_dwordx2 v[202:203], v[80:81], off offset:1456
	s_waitcnt vmcnt(0)
	v_lshlrev_b32_e32 v8, 16, v6
	v_and_b32_e32 v9, 0xffff0000, v6
	v_lshlrev_b32_e32 v6, 16, v7
	v_and_b32_e32 v7, 0xffff0000, v7
	v_pk_mul_f32 v[8:9], v[0:1], v[8:9] op_sel_hi:[0,1]
	v_pk_mul_f32 v[6:7], v[0:1], v[6:7] op_sel_hi:[0,1]
	v_pk_mul_f32 v[2:3], v[2:3], v[8:9]
	v_pk_mul_f32 v[4:5], v[4:5], v[6:7]
	v_cvt_pk_bf16_f32 v2, v2, v3
	v_cvt_pk_bf16_f32 v3, v4, v5
	global_store_dwordx2 v[80:81], v[2:3], off offset:1024
	s_nop 0
	v_lshlrev_b32_e32 v8, 16, v100
	v_and_b32_e32 v9, 0xffff0000, v100
	v_lshlrev_b32_e32 v100, 16, v101
	v_and_b32_e32 v101, 0xffff0000, v101
	v_pk_mul_f32 v[8:9], v[0:1], v[8:9] op_sel_hi:[0,1]
	v_pk_mul_f32 v[100:101], v[0:1], v[100:101] op_sel_hi:[0,1]
	v_pk_mul_f32 v[96:97], v[96:97], v[8:9]
	v_pk_mul_f32 v[98:99], v[98:99], v[100:101]
	v_cvt_pk_bf16_f32 v96, v96, v97
	v_cvt_pk_bf16_f32 v97, v98, v99
	global_store_dwordx2 v[80:81], v[96:97], off offset:1040
	s_nop 0
	v_lshlrev_b32_e32 v8, 16, v106
	v_and_b32_e32 v9, 0xffff0000, v106
	v_lshlrev_b32_e32 v106, 16, v107
	v_and_b32_e32 v107, 0xffff0000, v107
	v_pk_mul_f32 v[8:9], v[0:1], v[8:9] op_sel_hi:[0,1]
	v_pk_mul_f32 v[106:107], v[0:1], v[106:107] op_sel_hi:[0,1]
	v_pk_mul_f32 v[102:103], v[102:103], v[8:9]
	v_pk_mul_f32 v[104:105], v[104:105], v[106:107]
	v_cvt_pk_bf16_f32 v102, v102, v103
	v_cvt_pk_bf16_f32 v103, v104, v105
	global_store_dwordx2 v[80:81], v[102:103], off offset:1056
	s_nop 0
	v_lshlrev_b32_e32 v8, 16, v112
	v_and_b32_e32 v9, 0xffff0000, v112
	v_lshlrev_b32_e32 v112, 16, v113
	v_and_b32_e32 v113, 0xffff0000, v113
	v_pk_mul_f32 v[8:9], v[0:1], v[8:9] op_sel_hi:[0,1]
	v_pk_mul_f32 v[112:113], v[0:1], v[112:113] op_sel_hi:[0,1]
	v_pk_mul_f32 v[108:109], v[108:109], v[8:9]
	v_pk_mul_f32 v[110:111], v[110:111], v[112:113]
	v_cvt_pk_bf16_f32 v108, v108, v109
	v_cvt_pk_bf16_f32 v109, v110, v111
	global_store_dwordx2 v[80:81], v[108:109], off offset:1072
	s_nop 0
	v_lshlrev_b32_e32 v8, 16, v118
	v_and_b32_e32 v9, 0xffff0000, v118
	v_lshlrev_b32_e32 v118, 16, v119
	v_and_b32_e32 v119, 0xffff0000, v119
	v_pk_mul_f32 v[8:9], v[0:1], v[8:9] op_sel_hi:[0,1]
	v_pk_mul_f32 v[118:119], v[0:1], v[118:119] op_sel_hi:[0,1]
	v_pk_mul_f32 v[114:115], v[114:115], v[8:9]
	v_pk_mul_f32 v[116:117], v[116:117], v[118:119]
	v_cvt_pk_bf16_f32 v114, v114, v115
; DI unsigned pk2(float lo, float hi) { f32x2 v = {lo, hi}; bf16x2_t b = __builtin_convertvector(v, bf16x2_t); return __builtin_bit_cast(unsigned, b); }
; DI void s3_ssd_unit(LAS unsigned char* lds, int tid, const ScanCtx& C, int b, int vc) {
;     ...
; #pragma unroll
;     for (int h = 0; h < 4; ++h)
; #pragma unroll
;         for (int g4 = 0; g4 < 4; ++g4) {
;             const int p = pt * 32 + 8 * g4 + 4 * hi;
;             const f32x4 gv = *(const f32x4*)(C.ssmg + h * 64 + p);
;             u32x2* mp = (u32x2*)(C.MG + (size_t)rowq * DM + 512 + h * 64 + p);
;             const u32x2 v = *mp;
;             u32x2 w; w.x = pk2(bflo(v.x) * rn * gv.x, bfhi(v.x) * rn * gv.y); w.y = pk2(bflo(v.y) * rn * gv.z, bfhi(v.y) * rn * gv.w);
;             *mp = w;
;         }
	v_cvt_pk_bf16_f32 v115, v116, v117
	global_store_dwordx2 v[80:81], v[114:115], off offset:1152
	s_nop 0
	v_lshlrev_b32_e32 v8, 16, v124
	v_and_b32_e32 v9, 0xffff0000, v124
	v_lshlrev_b32_e32 v124, 16, v125
	v_and_b32_e32 v125, 0xffff0000, v125
	v_pk_mul_f32 v[8:9], v[0:1], v[8:9] op_sel_hi:[0,1]
	v_pk_mul_f32 v[124:125], v[0:1], v[124:125] op_sel_hi:[0,1]
	v_pk_mul_f32 v[120:121], v[120:121], v[8:9]
	v_pk_mul_f32 v[122:123], v[122:123], v[124:125]
	v_cvt_pk_bf16_f32 v120, v120, v121
	v_cvt_pk_bf16_f32 v121, v122, v123
	global_store_dwordx2 v[80:81], v[120:121], off offset:1168
	s_nop 0
	v_lshlrev_b32_e32 v8, 16, v130
	v_and_b32_e32 v9, 0xffff0000, v130
	v_lshlrev_b32_e32 v130, 16, v131
	v_and_b32_e32 v131, 0xffff0000, v131
	v_pk_mul_f32 v[8:9], v[0:1], v[8:9] op_sel_hi:[0,1]
	v_pk_mul_f32 v[130:131], v[0:1], v[130:131] op_sel_hi:[0,1]
	v_pk_mul_f32 v[126:127], v[126:127], v[8:9]
	v_pk_mul_f32 v[128:129], v[128:129], v[130:131]
	v_cvt_pk_bf16_f32 v126, v126, v127
	v_cvt_pk_bf16_f32 v127, v128, v129
	global_store_dwordx2 v[80:81], v[126:127], off offset:1184
	s_nop 0
	v_lshlrev_b32_e32 v8, 16, v136
	v_and_b32_e32 v9, 0xffff0000, v136
	v_lshlrev_b32_e32 v136, 16, v137
	v_and_b32_e32 v137, 0xffff0000, v137
	v_pk_mul_f32 v[8:9], v[0:1], v[8:9] op_sel_hi:[0,1]
	v_pk_mul_f32 v[136:137], v[0:1], v[136:137] op_sel_hi:[0,1]
	v_pk_mul_f32 v[132:133], v[132:133], v[8:9]
	v_pk_mul_f32 v[134:135], v[134:135], v[136:137]
	v_cvt_pk_bf16_f32 v132, v132, v133
	v_cvt_pk_bf16_f32 v133, v134, v135
	global_store_dwordx2 v[80:81], v[132:133], off offset:1200
	s_nop 0
	v_lshlrev_b32_e32 v8, 16, v142
	v_and_b32_e32 v9, 0xffff0000, v142
	v_lshlrev_b32_e32 v142, 16, v143
	v_and_b32_e32 v143, 0xffff0000, v143
	v_pk_mul_f32 v[8:9], v[0:1], v[8:9] op_sel_hi:[0,1]
	v_pk_mul_f32 v[142:143], v[0:1], v[142:143] op_sel_hi:[0,1]
	v_pk_mul_f32 v[138:139], v[138:139], v[8:9]
	v_pk_mul_f32 v[140:141], v[140:141], v[142:143]
	v_cvt_pk_bf16_f32 v138, v138, v139
	v_cvt_pk_bf16_f32 v139, v140, v141
	global_store_dwordx2 v[80:81], v[138:139], off offset:1280
	s_nop 0
	v_lshlrev_b32_e32 v8, 16, v164
	v_and_b32_e32 v9, 0xffff0000, v164
	v_lshlrev_b32_e32 v164, 16, v165
	v_and_b32_e32 v165, 0xffff0000, v165
	v_pk_mul_f32 v[8:9], v[0:1], v[8:9] op_sel_hi:[0,1]
	v_pk_mul_f32 v[164:165], v[0:1], v[164:165] op_sel_hi:[0,1]
	v_pk_mul_f32 v[160:161], v[160:161], v[8:9]
	v_pk_mul_f32 v[162:163], v[162:163], v[164:165]
	v_cvt_pk_bf16_f32 v160, v160, v161
	v_cvt_pk_bf16_f32 v161, v162, v163
	global_store_dwordx2 v[80:81], v[160:161], off offset:1296
	s_nop 0
	v_lshlrev_b32_e32 v8, 16, v172
	v_and_b32_e32 v9, 0xffff0000, v172
	v_lshlrev_b32_e32 v172, 16, v173
	v_and_b32_e32 v173, 0xffff0000, v173
	v_pk_mul_f32 v[8:9], v[0:1], v[8:9] op_sel_hi:[0,1]
	v_pk_mul_f32 v[172:173], v[0:1], v[172:173] op_sel_hi:[0,1]
	v_pk_mul_f32 v[168:169], v[168:169], v[8:9]
	v_pk_mul_f32 v[170:171], v[170:171], v[172:173]
	v_cvt_pk_bf16_f32 v168, v168, v169
	v_cvt_pk_bf16_f32 v169, v170, v171
	global_store_dwordx2 v[80:81], v[168:169], off offset:1312
	s_nop 0
	v_lshlrev_b32_e32 v8, 16, v178
	v_and_b32_e32 v9, 0xffff0000, v178
	v_lshlrev_b32_e32 v178, 16, v179
	v_and_b32_e32 v179, 0xffff0000, v179
	v_pk_mul_f32 v[8:9], v[0:1], v[8:9] op_sel_hi:[0,1]
	v_pk_mul_f32 v[178:179], v[0:1], v[178:179] op_sel_hi:[0,1]
	v_pk_mul_f32 v[174:175], v[174:175], v[8:9]
	v_pk_mul_f32 v[176:177], v[176:177], v[178:179]
	v_cvt_pk_bf16_f32 v174, v174, v175
	v_cvt_pk_bf16_f32 v175, v176, v177
	global_store_dwordx2 v[80:81], v[174:175], off offset:1328
	s_nop 0
	v_lshlrev_b32_e32 v8, 16, v184
	v_and_b32_e32 v9, 0xffff0000, v184
	v_lshlrev_b32_e32 v184, 16, v185
	v_and_b32_e32 v185, 0xffff0000, v185
	v_pk_mul_f32 v[8:9], v[0:1], v[8:9] op_sel_hi:[0,1]
	v_pk_mul_f32 v[184:185], v[0:1], v[184:185] op_sel_hi:[0,1]
	v_pk_mul_f32 v[180:181], v[180:181], v[8:9]
	v_pk_mul_f32 v[182:183], v[182:183], v[184:185]
	v_cvt_pk_bf16_f32 v180, v180, v181
	v_cvt_pk_bf16_f32 v181, v182, v183
	global_store_dwordx2 v[80:81], v[180:181], off offset:1408
	s_nop 0
	v_lshlrev_b32_e32 v8, 16, v190
	v_and_b32_e32 v9, 0xffff0000, v190
	v_lshlrev_b32_e32 v190, 16, v191
	v_and_b32_e32 v191, 0xffff0000, v191
	v_pk_mul_f32 v[8:9], v[0:1], v[8:9] op_sel_hi:[0,1]
	v_pk_mul_f32 v[190:191], v[0:1], v[190:191] op_sel_hi:[0,1]
	v_pk_mul_f32 v[186:187], v[186:187], v[8:9]
	v_pk_mul_f32 v[188:189], v[188:189], v[190:191]
	v_cvt_pk_bf16_f32 v186, v186, v187
	v_cvt_pk_bf16_f32 v187, v188, v189
	global_store_dwordx2 v[80:81], v[186:187], off offset:1424
	s_nop 0
	v_lshlrev_b32_e32 v8, 16, v196
	v_and_b32_e32 v9, 0xffff0000, v196
	v_lshlrev_b32_e32 v196, 16, v197
	v_and_b32_e32 v197, 0xffff0000, v197
	v_pk_mul_f32 v[8:9], v[0:1], v[8:9] op_sel_hi:[0,1]
	v_pk_mul_f32 v[196:197], v[0:1], v[196:197] op_sel_hi:[0,1]
	v_pk_mul_f32 v[192:193], v[192:193], v[8:9]
	v_pk_mul_f32 v[194:195], v[194:195], v[196:197]
	v_cvt_pk_bf16_f32 v192, v192, v193
	v_cvt_pk_bf16_f32 v193, v194, v195
	global_store_dwordx2 v[80:81], v[192:193], off offset:1440
	s_nop 0
	v_readlane_b32 s0, v253, 34
	s_add_i32 s6, s6, s0
	v_readlane_b32 s0, v253, 63
	s_cmp_ge_i32 s6, s0
	v_lshlrev_b32_e32 v8, 16, v202
	v_and_b32_e32 v9, 0xffff0000, v202
	v_lshlrev_b32_e32 v202, 16, v203
	v_and_b32_e32 v203, 0xffff0000, v203
	v_pk_mul_f32 v[8:9], v[0:1], v[8:9] op_sel_hi:[0,1]
	v_pk_mul_f32 v[0:1], v[0:1], v[202:203] op_sel_hi:[0,1]
	v_pk_mul_f32 v[198:199], v[198:199], v[8:9]
	v_pk_mul_f32 v[0:1], v[200:201], v[0:1]
	v_cvt_pk_bf16_f32 v198, v198, v199
	v_cvt_pk_bf16_f32 v199, v0, v1
	global_store_dwordx2 v[80:81], v[198:199], off offset:1456
	v_mov_b32_e32 v2, v198
	v_mov_b32_e32 v3, v199
	v_mov_b32_e32 v4, v200
	v_mov_b32_e32 v5, v201
	v_mov_b32_e32 v6, v202
	v_mov_b32_e32 v7, v203
	s_cbranch_scc1 .LBB0_620
